# P2 steep attention items dequeued longest-first; redundant second accumulator zeroing removed in 7 GEMM bodies; P6 epilogue as v002
# speedup vs baseline: 1.0060x; 1.0054x over previous
;     __host__ __device__ bool next(int i, Unit& u) const { return i < cnt ? so.next(base + i, u) : false; }
;     __host__ __device__ bool next(int i, Unit& u) const { const int L = i * G + c; if (L >= 32) return false; u.g = L >> 3; u.pm = L & 7; u.pn = 0; return true; }
;   __device__ __forceinline__ bool next(int i,AttnUnit&u)const{ if(i>=4)return false; const int s=vcu&7; u.bh=vcu>>3; u.qb=(i==0)?s:(i==1)?15-s:(i==2)?16+s:31-s; return true; }
; template <class Epi, class Sched, bool ALIGN_EPI = false, bool SP2 = false>
; __device__ __forceinline__ void gemm_phase(PG8_LAS unsigned char* lds, const Gemm g, const Sched& S, const Epi& E) {
;     ...
;         const bool has_next = S.next(ui + 1, nxt);
;         const char* nA = has_next ? (const char*)(g.A + (size_t)nxt.g * g.gsA) + (size_t)nxt.pm * tstepA : cA; const char* nB = has_next ? (const char*)(g.Bt + (size_t)nxt.g * g.gsB) + (size_t)nxt.pn * tstepB : cB;
;         for (int t = 0; t < nt; t += 2) {
;             if constexpr (Epi::MIDK) { if (t == (nt >> 1)) { asm volatile("s_waitcnt vmcnt(0)" ::: "memory"); E.mid(acc, cur, wr, wc, fr, fq); asm volatile("s_waitcnt vmcnt(0)" ::: "memory"); } }
;             const bool last = (t == nt - 2);
;             const char* a1 = cA + (size_t)(t + 1) * kstep;
;             const char* a2 = last ? nA : cA + (size_t)(t + 2) * kstep; const char* b2 = last ? nB : cB + (size_t)(t + 2) * kstep;
;             const char* a3 = a2 + kstep; const char* b3 = b2 + kstep;
;     ...
; #pragma unroll
;         for (int a = 0; a < 2; ++a)
; #pragma unroll
;             for (int b = 0; b < 2; ++b)
; #pragma unroll
;                 for (int m = 0; m < 4; ++m)
; #pragma unroll
;                     for (int n = 0; n < 2; ++n) acc[a][b][m][n] = (f32x4){0.f, 0.f, 0.f, 0.f};
.LBB0_84:
	s_ashr_i32 s25, s24, 31
	s_lshl_b64 s[26:27], s[24:25], 20
	s_add_u32 s26, s37, s26
	s_addc_u32 s27, s38, s27
	s_ashr_i32 s23, s22, 31
	s_lshl_b64 s[28:29], s[22:23], 20
	s_add_u32 s28, s39, s28
	v_mov_b32_e32 v127, 0
	s_addc_u32 s29, s44, s29
	s_and_b64 vcc, exec, s[6:7]
	v_mov_b32_e32 v126, v127
	v_mov_b32_e32 v125, v127
	v_mov_b32_e32 v124, v127
	v_mov_b32_e32 v123, v127
	v_mov_b32_e32 v122, v127
	v_mov_b32_e32 v121, v127
	v_mov_b32_e32 v120, v127
	v_mov_b32_e32 v111, v127
	v_mov_b32_e32 v110, v127
	v_mov_b32_e32 v109, v127
	v_mov_b32_e32 v108, v127
	v_mov_b32_e32 v107, v127
	v_mov_b32_e32 v106, v127
	v_mov_b32_e32 v105, v127
	v_mov_b32_e32 v104, v127
	v_mov_b32_e32 v95, v127
	v_mov_b32_e32 v94, v127
	v_mov_b32_e32 v93, v127
	v_mov_b32_e32 v92, v127
	v_mov_b32_e32 v91, v127
	v_mov_b32_e32 v90, v127
	v_mov_b32_e32 v89, v127
	v_mov_b32_e32 v88, v127
	v_mov_b32_e32 v79, v127
	v_mov_b32_e32 v78, v127
	v_mov_b32_e32 v77, v127
	v_mov_b32_e32 v76, v127
	v_mov_b32_e32 v75, v127
	v_mov_b32_e32 v74, v127
	v_mov_b32_e32 v73, v127
	v_mov_b32_e32 v72, v127
	v_mov_b32_e32 v119, v127
	v_mov_b32_e32 v118, v127
	v_mov_b32_e32 v117, v127
	v_mov_b32_e32 v116, v127
	v_mov_b32_e32 v115, v127
	v_mov_b32_e32 v114, v127
	v_mov_b32_e32 v113, v127
	v_mov_b32_e32 v112, v127
	v_mov_b32_e32 v103, v127
	v_mov_b32_e32 v102, v127
	v_mov_b32_e32 v101, v127
	v_mov_b32_e32 v100, v127
	v_mov_b32_e32 v99, v127
	v_mov_b32_e32 v98, v127
	v_mov_b32_e32 v97, v127
	v_mov_b32_e32 v96, v127
	v_mov_b32_e32 v87, v127
	v_mov_b32_e32 v86, v127
	v_mov_b32_e32 v85, v127
	v_mov_b32_e32 v84, v127
	v_mov_b32_e32 v83, v127
	v_mov_b32_e32 v82, v127
	v_mov_b32_e32 v81, v127
	v_mov_b32_e32 v80, v127
	v_mov_b32_e32 v71, v127
	v_mov_b32_e32 v70, v127
	v_mov_b32_e32 v69, v127
	v_mov_b32_e32 v68, v127
	v_mov_b32_e32 v67, v127
	v_mov_b32_e32 v66, v127
	v_mov_b32_e32 v65, v127
	v_mov_b32_e32 v64, v127
	v_mov_b32_e32 v63, v127
	v_mov_b32_e32 v62, v127
	v_mov_b32_e32 v61, v127
	v_mov_b32_e32 v60, v127
	v_mov_b32_e32 v59, v127
	v_mov_b32_e32 v58, v127
	v_mov_b32_e32 v57, v127
	v_mov_b32_e32 v56, v127
	v_mov_b32_e32 v47, v127
	v_mov_b32_e32 v46, v127
	v_mov_b32_e32 v45, v127
	v_mov_b32_e32 v44, v127
	v_mov_b32_e32 v43, v127
	v_mov_b32_e32 v42, v127
	v_mov_b32_e32 v41, v127
	v_mov_b32_e32 v40, v127
	v_mov_b32_e32 v31, v127
	v_mov_b32_e32 v30, v127
	v_mov_b32_e32 v29, v127
	v_mov_b32_e32 v28, v127
	v_mov_b32_e32 v27, v127
	v_mov_b32_e32 v26, v127
	v_mov_b32_e32 v25, v127
	v_mov_b32_e32 v24, v127
	v_mov_b32_e32 v15, v127
	v_mov_b32_e32 v14, v127
	v_mov_b32_e32 v13, v127
	v_mov_b32_e32 v12, v127
	v_mov_b32_e32 v11, v127
	v_mov_b32_e32 v10, v127
	v_mov_b32_e32 v9, v127
	v_mov_b32_e32 v8, v127
	v_mov_b32_e32 v55, v127
	v_mov_b32_e32 v54, v127
	v_mov_b32_e32 v53, v127
	v_mov_b32_e32 v52, v127
	v_mov_b32_e32 v51, v127
	v_mov_b32_e32 v50, v127
	v_mov_b32_e32 v49, v127
	v_mov_b32_e32 v48, v127
	v_mov_b32_e32 v39, v127
	v_mov_b32_e32 v38, v127
	v_mov_b32_e32 v37, v127
	v_mov_b32_e32 v36, v127
	v_mov_b32_e32 v35, v127
	v_mov_b32_e32 v34, v127
	v_mov_b32_e32 v33, v127
	v_mov_b32_e32 v32, v127
	v_mov_b32_e32 v23, v127
	v_mov_b32_e32 v22, v127
	v_mov_b32_e32 v21, v127
	v_mov_b32_e32 v20, v127
	v_mov_b32_e32 v19, v127
	v_mov_b32_e32 v18, v127
	v_mov_b32_e32 v17, v127
	v_mov_b32_e32 v16, v127
	v_mov_b32_e32 v7, v127
	v_mov_b32_e32 v6, v127
	v_mov_b32_e32 v5, v127
	v_mov_b32_e32 v4, v127
	v_mov_b32_e32 v3, v127
	v_mov_b32_e32 v2, v127
	s_waitcnt lgkmcnt(0)
	v_mov_b32_e32 v1, v127
	v_mov_b32_e32 v0, v127
	s_cbranch_vccnz .LBB0_87
	s_and_b64 s[34:35], s[8:9], exec
	s_cselect_b32 s11, s27, s31
	s_cselect_b32 s23, s26, s30
	s_cselect_b32 s25, s29, s13
	s_cselect_b32 s40, s28, s12
	s_add_u32 s41, s12, 0x100
	s_addc_u32 s42, s13, 0
	s_add_u32 s12, s30, 0x80080
	s_addc_u32 s13, s31, 0
	s_mov_b32 s30, 0

; template <class Epi, class Sched, bool ALIGN_EPI = false, bool SP2 = false>
; __device__ __forceinline__ void gemm_phase(PG8_LAS unsigned char* lds, const Gemm g, const Sched& S, const Epi& E) {
;     ...
; #pragma unroll
;         for (int a = 0; a < 2; ++a)
; #pragma unroll
;             for (int b = 0; b < 2; ++b)
; #pragma unroll
;                 for (int m = 0; m < 4; ++m)
; #pragma unroll
;                     for (int n = 0; n < 2; ++n) acc[a][b][m][n] = (f32x4){0.f, 0.f, 0.f, 0.f};
.LBB0_252:
	s_add_i32 s55, s55, 1
	s_mul_i32 s28, s55, s33
	s_add_i32 s28, s28, s2
	s_mov_b32 s19, s64
	s_mov_b32 s30, s63
	s_and_b32 s64, s28, 7
	s_ashr_i32 s63, s28, 3
	s_cmp_lt_i32 s28, 32
	s_cselect_b64 s[34:35], -1, 0
	s_and_b64 s[28:29], s[34:35], exec
	s_cselect_b32 s30, s63, s30
	s_cselect_b32 s28, s64, s19
	s_ashr_i32 s31, s30, 31
	s_lshl_b64 s[44:45], s[30:31], 9
	s_add_u32 s19, s37, s44
	s_addc_u32 s44, s38, s45
	s_ashr_i32 s29, s28, 31
	s_lshl_b64 s[28:29], s[28:29], 19
	s_add_u32 s28, s19, s28
	s_addc_u32 s29, s44, s29
	s_lshl_b64 s[30:31], s[30:31], 17
	s_add_u32 s30, s39, s30
	v_mov_b32_e32 v127, 0
	s_addc_u32 s31, s46, s31
	s_and_b64 vcc, exec, s[4:5]
	v_mov_b32_e32 v126, v127
	v_mov_b32_e32 v125, v127
	v_mov_b32_e32 v124, v127
	v_mov_b32_e32 v123, v127
	v_mov_b32_e32 v122, v127
	v_mov_b32_e32 v121, v127
	v_mov_b32_e32 v120, v127
	v_mov_b32_e32 v111, v127
	v_mov_b32_e32 v110, v127
	v_mov_b32_e32 v109, v127
	v_mov_b32_e32 v108, v127
	v_mov_b32_e32 v107, v127
	v_mov_b32_e32 v106, v127
	v_mov_b32_e32 v105, v127
	v_mov_b32_e32 v104, v127
	v_mov_b32_e32 v95, v127
	v_mov_b32_e32 v94, v127
	v_mov_b32_e32 v93, v127
	v_mov_b32_e32 v92, v127
	v_mov_b32_e32 v91, v127
	v_mov_b32_e32 v90, v127
	v_mov_b32_e32 v89, v127
	v_mov_b32_e32 v88, v127
	v_mov_b32_e32 v79, v127
	v_mov_b32_e32 v78, v127
	v_mov_b32_e32 v77, v127
	v_mov_b32_e32 v76, v127
	v_mov_b32_e32 v75, v127
	v_mov_b32_e32 v74, v127
	v_mov_b32_e32 v73, v127
	v_mov_b32_e32 v72, v127
	v_mov_b32_e32 v119, v127
	v_mov_b32_e32 v118, v127
	v_mov_b32_e32 v117, v127
	v_mov_b32_e32 v116, v127
	v_mov_b32_e32 v115, v127
	v_mov_b32_e32 v114, v127
	v_mov_b32_e32 v113, v127
	v_mov_b32_e32 v112, v127
	v_mov_b32_e32 v103, v127
	v_mov_b32_e32 v102, v127
	v_mov_b32_e32 v101, v127
	v_mov_b32_e32 v100, v127
	v_mov_b32_e32 v99, v127
	v_mov_b32_e32 v98, v127
	v_mov_b32_e32 v97, v127
	v_mov_b32_e32 v96, v127
	v_mov_b32_e32 v87, v127
	v_mov_b32_e32 v86, v127
	v_mov_b32_e32 v85, v127
	v_mov_b32_e32 v84, v127
	v_mov_b32_e32 v83, v127
	v_mov_b32_e32 v82, v127
	v_mov_b32_e32 v81, v127
	v_mov_b32_e32 v80, v127
	v_mov_b32_e32 v71, v127
	v_mov_b32_e32 v70, v127
	v_mov_b32_e32 v69, v127
	v_mov_b32_e32 v68, v127
	v_mov_b32_e32 v67, v127
	v_mov_b32_e32 v66, v127
	v_mov_b32_e32 v65, v127
	v_mov_b32_e32 v64, v127
	v_mov_b32_e32 v63, v127
	v_mov_b32_e32 v62, v127
	v_mov_b32_e32 v61, v127
	v_mov_b32_e32 v60, v127
	v_mov_b32_e32 v59, v127
	v_mov_b32_e32 v58, v127
	v_mov_b32_e32 v57, v127
	v_mov_b32_e32 v56, v127
	v_mov_b32_e32 v47, v127
	v_mov_b32_e32 v46, v127
	v_mov_b32_e32 v45, v127
	v_mov_b32_e32 v44, v127
	v_mov_b32_e32 v43, v127
	v_mov_b32_e32 v42, v127
	v_mov_b32_e32 v41, v127
	v_mov_b32_e32 v40, v127
	v_mov_b32_e32 v31, v127
	v_mov_b32_e32 v30, v127
	v_mov_b32_e32 v29, v127
	v_mov_b32_e32 v28, v127
	v_mov_b32_e32 v27, v127
	v_mov_b32_e32 v26, v127
	v_mov_b32_e32 v25, v127
	v_mov_b32_e32 v24, v127
	v_mov_b32_e32 v15, v127
	v_mov_b32_e32 v14, v127
	v_mov_b32_e32 v13, v127
	v_mov_b32_e32 v12, v127
	v_mov_b32_e32 v11, v127
	v_mov_b32_e32 v10, v127
	v_mov_b32_e32 v9, v127
	v_mov_b32_e32 v8, v127
	v_mov_b32_e32 v55, v127
	v_mov_b32_e32 v54, v127
	v_mov_b32_e32 v53, v127
	v_mov_b32_e32 v52, v127
	v_mov_b32_e32 v51, v127
	v_mov_b32_e32 v50, v127
	v_mov_b32_e32 v49, v127
	v_mov_b32_e32 v48, v127
	v_mov_b32_e32 v39, v127
	v_mov_b32_e32 v38, v127
	v_mov_b32_e32 v37, v127
	v_mov_b32_e32 v36, v127
	v_mov_b32_e32 v35, v127
	v_mov_b32_e32 v34, v127
	v_mov_b32_e32 v33, v127
	v_mov_b32_e32 v32, v127
	v_mov_b32_e32 v23, v127
	v_mov_b32_e32 v22, v127
	v_mov_b32_e32 v21, v127
	v_mov_b32_e32 v20, v127
	v_mov_b32_e32 v19, v127
	v_mov_b32_e32 v18, v127
	v_mov_b32_e32 v17, v127
	v_mov_b32_e32 v16, v127
	v_mov_b32_e32 v7, v127
	v_mov_b32_e32 v6, v127
	v_mov_b32_e32 v5, v127
	v_mov_b32_e32 v4, v127
	v_mov_b32_e32 v3, v127
	v_mov_b32_e32 v2, v127
	v_mov_b32_e32 v1, v127
	v_mov_b32_e32 v0, v127
	s_cbranch_vccnz .LBB0_255
	s_and_b64 s[44:45], s[34:35], exec
	s_cselect_b32 s19, s29, s43
	s_cselect_b32 s65, s28, s42
	s_cselect_b32 s66, s31, s41
	s_cselect_b32 s67, s30, s40
	s_add_u32 s68, s40, 0x100
	s_addc_u32 s69, s41, 0
	s_add_u32 s40, s42, 0x40080
	s_addc_u32 s41, s43, 0
	s_mov_b32 s42, 0

; #define INP(i) ((const float*)ldp(ptab, (i)))
; __global__ void __launch_bounds__(NWAVES * 64, 2) fwd_megakernel(Args args) {
;     ...
;             if (threadIdx.x == 0) *qw = first_ ? (unsigned)bx : (unsigned)G + __hip_atomic_fetch_add(qctr + rep_, 1u, __ATOMIC_RELAXED, __HIP_MEMORY_SCOPE_AGENT);
;             first_ = false;
;             __syncthreads();
;             const unsigned pidx = __builtin_amdgcn_readfirstlane(*qw);
;             if (pidx >= 1152u) break;
;             if (pidx < 512u && (pidx & 1u) == 1u) {
;                 const int ci = (int)(pidx >> 1);
;                 constexpr int J_UP = (DM / 64) * (FF / 32), J_DN = (FF / 64) * (DM / 32), J_OUT = (DM / 64) * (DM / 32), J_PG = J_OUT, J_PLE = (PLE / 64) * (DM / 32), J_ALL = J_UP + J_DN + J_OUT + J_PG + J_PLE;
;                 static_assert(J_ALL == 256 * 81, "conversion items");
; #pragma unroll 1
;                 for (int k2 = 0; k2 < 11; ++k2) { const int wi = wave + 8 * k2; if (wi >= 81) break; int r = ci * 81 + wi;
;                     if (r < J_UP) { p0_transpose_item(INP(15), DM, FF, WSP(bfu, WS_WUP), INP(14), nullptr, r, lane); continue; } r -= J_UP;
;                     if (r < J_DN) { p0_transpose_item(INP(16), FF, DM, WSP(bfu, WS_WDN), nullptr, nullptr, r, lane); continue; } r -= J_DN;
;                     if (r < J_OUT) { p0_transpose_item(INP(13), DM, DM, WSP(bfu, WS_WOUT), nullptr, nullptr, r, lane); continue; } r -= J_OUT;
;                     if (r < J_PG) { p0_transpose_item(INP(19), DM, DM, WSP(bfu, WS_WPG), INP(17), nullptr, r, lane); continue; } r -= J_PG;
;                     p0_transpose_item(INP(18), PLE, DM, WSP(bfu, WS_WPLE), nullptr, nullptr, r, lane); }
;                 { const f32x4* p4 = (const f32x4*)INP(1); uint2* pb = (uint2*)WSP(bfu, WS_PB);
; #pragma unroll
;                   for (int k2 = 0; k2 < 4; ++k2) { const int i = ci * 2048 + k2 * 512 + (int)threadIdx.x; const f32x4 v = __builtin_nontemporal_load(p4 + i); pb[i] = make_uint2(pk2(v[0], v[1]), pk2(v[2], v[3])); } }
;                 __syncthreads(); continue; }
;             const unsigned n = (pidx < 512u) ? (pidx >> 1) : pidx - 256u;
;             if (n >= 768u) {
;                 const int pc = (int)(n - 768u);
; #pragma unroll 1
;                 for (int k2 = 0; k2 < 2; ++k2) { const int i = pc * 1024 + k2 * 512 + (int)threadIdx.x; const int ch = i & 127, tb = (i >> 7) * 8, gidx = ch >> 5;
.LBB0_269:
	s_or_b64 exec, exec, s[8:9]
	s_waitcnt lgkmcnt(0)
	s_barrier
	ds_read_b32 v0, v239
	s_mov_b64 s[0:1], -1
	s_waitcnt lgkmcnt(0)
	v_readfirstlane_b32 s85, v0
	s_cmpk_gt_u32 s85, 0x47f
	s_cbranch_scc1 .LBB0_264
	s_and_b32 s0, s85, 0x601
	s_cmp_lg_u32 s0, 1
	s_mov_b64 s[0:1], -1
	s_cbranch_scc0 .LBB0_473
	s_lshr_b32 s0, s85, 1
	s_add_i32 s1, s85, 0xffffff00
	s_cmpk_gt_u32 s85, 0x1ff
	s_cselect_b32 s86, s1, s0
	s_cmpk_lt_u32 s86, 0x300
	s_mov_b64 s[0:1], -1
	s_cbranch_scc0 .LBB0_338
	s_cmpk_lt_u32 s86, 0x200
	s_cselect_b64 s[8:9], -1, 0
	s_cmpk_gt_u32 s86, 0x1ff
	s_cbranch_scc0 .LBB0_274
	s_add_i32 s0, s86, 0xfffffe00
	s_bfe_u32 s78, s0, 0x50001
	s_lshr_b32 s64, s0, 6
	s_sub_i32 s64, 3, s64
	s_and_b32 s17, s86, 1
	s_mov_b64 s[0:1], 0
.LBB0_274:
	s_andn2_b64 vcc, exec, s[0:1]
	s_mov_b32 s16, 0
	s_cbranch_vccnz .LBB0_276
	s_and_b32 s0, s86, 3
	s_lshr_b32 s78, s86, 4
	s_bfe_u32 s16, s86, 0x10003
	s_bfe_u32 s17, s86, 0x10002
	s_or_b32 s64, s0, 4
.LBB0_276:
	s_lshl_b32 s0, s17, 3
	s_add_i32 s67, s64, s0
	s_add_i32 s0, s64, 1
	v_cvt_f32_u32_e32 v0, s0
	s_mov_b32 s5, 0x42fc0000
	s_sub_i32 s38, 31, s78
	v_readlane_b32 s4, v255, 13
	v_cmp_lt_f32_e32 vcc, s5, v0
	s_and_b64 s[0:1], vcc, exec
	s_cselect_b32 s0, 0xffffffc0, 0
	v_cndmask_b32_e32 v1, 0, v243, vcc
	v_sub_f32_e32 v0, v1, v0
	v_exp_f32_e32 v0, v0
	s_lshl_b32 s10, s67, 1
	v_ldexp_f32 v6, v0, s0
	s_lshl_b64 s[0:1], s[10:11], 2
	s_add_u32 s0, s4, s0
	v_readlane_b32 s4, v255, 14
	s_addc_u32 s1, s4, s1
	v_mov_b64_e32 v[0:1], s[0:1]
	flat_load_dword v2, v[0:1] sc1
	flat_load_dword v4, v[0:1] offset:4 sc1
	flat_load_dword v3, v[0:1] offset:128 sc1
	flat_load_dword v5, v[0:1] offset:132 sc1
	s_mov_b32 s0, 0xf800000
	v_mul_f32_e32 v245, 0x3fb8aa3b, v6
	s_waitcnt vmcnt(0) lgkmcnt(0)
	v_pk_add_f32 v[0:1], v[2:3], v[4:5]
	s_nop 0
	v_mul_f32_e32 v0, v0, v1
	v_cmp_gt_f32_e32 vcc, s0, v0
	v_mul_f32_e32 v1, 0x4f800000, v0
	s_nop 0
	v_cndmask_b32_e32 v0, v0, v1, vcc
	v_sqrt_f32_e32 v1, v0
	s_nop 0
	v_add_u32_e32 v2, -1, v1
	v_fma_f32 v3, -v2, v1, v0
	v_cmp_ge_f32_e64 s[0:1], 0, v3
	v_add_u32_e32 v3, 1, v1
	s_nop 0
	v_cndmask_b32_e64 v2, v1, v2, s[0:1]
	v_fma_f32 v1, -v3, v1, v0
	v_cmp_lt_f32_e64 s[0:1], 0, v1
	s_nop 1
	v_cndmask_b32_e64 v1, v2, v3, s[0:1]
	v_mul_f32_e32 v2, 0x37800000, v1
	v_cndmask_b32_e32 v1, v1, v2, vcc
	v_cmp_class_f32_e32 vcc, v0, v241
	s_nop 1
	v_cndmask_b32_e32 v0, v1, v0, vcc
	v_cmp_lt_f32_e32 vcc, s5, v245
	s_and_b64 s[0:1], vcc, exec
	s_cselect_b32 s0, 0xffffffc0, 0
	v_cndmask_b32_e32 v2, 0, v243, vcc
	v_fmac_f32_e32 v2, 0xbfb8aa3b, v6
	v_exp_f32_e32 v2, v2
	v_mov_b32_e32 v1, 0x3c23d70a
	v_fmamk_f32 v0, v0, 0x3f828f5c, v1
	v_fmaak_f32 v1, 2.0, v0, 0x42000000
	v_ldexp_f32 v2, v2, s0
	v_sub_f32_e32 v2, 1.0, v2
	s_mov_b32 s0, 0x800000
	v_cmp_gt_f32_e32 vcc, s0, v2
	s_and_b64 s[0:1], vcc, exec
	s_cselect_b32 s0, 32, 0
	v_ldexp_f32 v2, v2, s0
	v_log_f32_e32 v2, v2
	v_cndmask_b32_e32 v3, 0, v242, vcc
	s_lshl_b32 s4, s38, 8
	v_min_f32_e32 v0, 0x42700000, v0
	v_sub_f32_e32 v2, v2, v3
	v_sub_f32_e32 v1, v1, v2
	v_div_scale_f32 v2, s[0:1], v245, v245, v1
	v_rcp_f32_e32 v3, v2
	v_readfirstlane_b32 s5, v0
	v_fma_f32 v4, -v2, v3, 1.0
	v_fmac_f32_e32 v3, v4, v3
	v_div_scale_f32 v4, vcc, v1, v245, v1
	v_mul_f32_e32 v5, v4, v3
	v_fma_f32 v6, -v2, v5, v4
	v_fmac_f32_e32 v5, v6, v3
	v_fma_f32 v2, -v2, v5, v4
	v_div_fmas_f32 v2, v2, v3, v5
	v_div_fixup_f32 v1, v2, v245, v1
	v_ceil_f32_e32 v1, v1
	v_min_f32_e32 v1, 0x49800000, v1
	v_cvt_i32_f32_e32 v1, v1
	s_nop 0
	v_readfirstlane_b32 s0, v1
	s_sub_i32 s0, s4, s0
	s_add_i32 s1, s0, 1
	s_ashr_i32 s1, s1, 6
	s_and_b32 s1, s1, -2
	s_cmp_gt_i32 s0, -1
	s_cselect_b32 s66, s1, 0
	s_lshl_b32 s0, s38, 2
	s_sub_i32 s10, s0, s66
	s_add_i32 s10, s10, 4
	s_cmp_gt_i32 s10, 15
	s_cselect_b64 s[0:1], -1, 0
	s_and_b64 s[62:63], s[8:9], s[0:1]
	s_cmp_lg_u32 s16, 0
	s_cselect_b64 s[8:9], -1, 0
	s_cmp_eq_u32 s16, 0
	s_cselect_b64 s[38:39], -1, 0
	s_or_b64 s[38:39], s[38:39], s[62:63]
	s_mov_b64 s[0:1], -1
	s_and_b64 vcc, exec, s[38:39]
	s_cbranch_vccnz .LBB0_278
	s_mov_b64 s[0:1], 0
	s_barrier

;     __host__ __device__ bool next(int i, Unit& u) const { return i < cnt ? so.next(base + i, u) : false; }
;     __host__ __device__ bool next(int i, Unit& u) const { const int L = i * G + c; if (L >= 32) return false; u.g = L >> 3; u.pm = L & 7; u.pn = 0; return true; }
;   __device__ __forceinline__ bool next(int i,AttnUnit&u)const{ if(i>=4)return false; const int s=vcu&7; u.bh=vcu>>3; u.qb=(i==0)?s:(i==1)?15-s:(i==2)?16+s:31-s; return true; }
;     __device__ __forceinline__ void mid(f32x4 (&acc)[2][2][4][2], const Unit& u, int wr, int wc, int fr, int fq) const {
;         const int col0 = u.pn * BM + wc * 32 + 8 * fq, row0 = u.pm * BM + wr * 64 + fr;
;         unsigned long long ro_ = ((unsigned long long)row0 * 2048 + col0) * 2; asm volatile("" : "+v"(ro_));
; template <class Epi, class Sched, bool ALIGN_EPI = false, bool SP2 = false>
; __device__ __forceinline__ void gemm_phase(PG8_LAS unsigned char* lds, const Gemm g, const Sched& S, const Epi& E) {
;     ...
;         const bool has_next = S.next(ui + 1, nxt);
;         const char* nA = has_next ? (const char*)(g.A + (size_t)nxt.g * g.gsA) + (size_t)nxt.pm * tstepA : cA; const char* nB = has_next ? (const char*)(g.Bt + (size_t)nxt.g * g.gsB) + (size_t)nxt.pn * tstepB : cB;
;         for (int t = 0; t < nt; t += 2) {
;             if constexpr (Epi::MIDK) { if (t == (nt >> 1)) { asm volatile("s_waitcnt vmcnt(0)" ::: "memory"); E.mid(acc, cur, wr, wc, fr, fq); asm volatile("s_waitcnt vmcnt(0)" ::: "memory"); } }
;             const bool last = (t == nt - 2);
;             const char* a1 = cA + (size_t)(t + 1) * kstep;
;             const char* a2 = last ? nA : cA + (size_t)(t + 2) * kstep; const char* b2 = last ? nB : cB + (size_t)(t + 2) * kstep;
;             const char* a3 = a2 + kstep; const char* b3 = b2 + kstep;
;     ...
; #pragma unroll
;         for (int a = 0; a < 2; ++a)
; #pragma unroll
;             for (int b = 0; b < 2; ++b)
; #pragma unroll
;                 for (int m = 0; m < 4; ++m)
; #pragma unroll
;                     for (int n = 0; n < 2; ++n) acc[a][b][m][n] = (f32x4){0.f, 0.f, 0.f, 0.f};
.LBB0_670:
	s_ashr_i32 s31, s30, 31
	s_lshl_b64 s[34:35], s[30:31], 20
	s_add_u32 s34, s39, s34
	s_addc_u32 s35, s48, s35
	s_ashr_i32 s29, s28, 31
	s_lshl_b64 s[40:41], s[28:29], 20
	s_add_u32 s40, s49, s40
	v_mov_b32_e32 v127, 0
	s_addc_u32 s41, s50, s41
	s_andn2_b64 vcc, exec, s[18:19]
	v_lshl_or_b32 v176, s47, 8, v190
	v_lshl_add_u32 v178, s46, 8, v188
	v_mov_b32_e32 v126, v127
	v_mov_b32_e32 v125, v127
	v_mov_b32_e32 v124, v127
	v_mov_b32_e32 v123, v127
	v_mov_b32_e32 v122, v127
	v_mov_b32_e32 v121, v127
	v_mov_b32_e32 v120, v127
	v_mov_b32_e32 v111, v127
	v_mov_b32_e32 v110, v127
	v_mov_b32_e32 v109, v127
	v_mov_b32_e32 v108, v127
	v_mov_b32_e32 v107, v127
	v_mov_b32_e32 v106, v127
	v_mov_b32_e32 v105, v127
	v_mov_b32_e32 v104, v127
	v_mov_b32_e32 v95, v127
	v_mov_b32_e32 v94, v127
	v_mov_b32_e32 v93, v127
	v_mov_b32_e32 v92, v127
	v_mov_b32_e32 v91, v127
	v_mov_b32_e32 v90, v127
	v_mov_b32_e32 v89, v127
	v_mov_b32_e32 v88, v127
	v_mov_b32_e32 v79, v127
	v_mov_b32_e32 v78, v127
	v_mov_b32_e32 v77, v127
	v_mov_b32_e32 v76, v127
	v_mov_b32_e32 v75, v127
	v_mov_b32_e32 v74, v127
	v_mov_b32_e32 v73, v127
	v_mov_b32_e32 v72, v127
	v_mov_b32_e32 v119, v127
	v_mov_b32_e32 v118, v127
	v_mov_b32_e32 v117, v127
	v_mov_b32_e32 v116, v127
	v_mov_b32_e32 v115, v127
	v_mov_b32_e32 v114, v127
	v_mov_b32_e32 v113, v127
	v_mov_b32_e32 v112, v127
	v_mov_b32_e32 v103, v127
	v_mov_b32_e32 v102, v127
	v_mov_b32_e32 v101, v127
	v_mov_b32_e32 v100, v127
	v_mov_b32_e32 v99, v127
	v_mov_b32_e32 v98, v127
	v_mov_b32_e32 v97, v127
	v_mov_b32_e32 v96, v127
	v_mov_b32_e32 v87, v127
	v_mov_b32_e32 v86, v127
	v_mov_b32_e32 v85, v127
	v_mov_b32_e32 v84, v127
	v_mov_b32_e32 v83, v127
	v_mov_b32_e32 v82, v127
	v_mov_b32_e32 v81, v127
	v_mov_b32_e32 v80, v127
	v_mov_b32_e32 v71, v127
	v_mov_b32_e32 v70, v127
	v_mov_b32_e32 v69, v127
	v_mov_b32_e32 v68, v127
	v_mov_b32_e32 v67, v127
	v_mov_b32_e32 v66, v127
	v_mov_b32_e32 v65, v127
	v_mov_b32_e32 v64, v127
	v_mov_b32_e32 v63, v127
	v_mov_b32_e32 v62, v127
	v_mov_b32_e32 v61, v127
	v_mov_b32_e32 v60, v127
	v_mov_b32_e32 v59, v127
	v_mov_b32_e32 v58, v127
	v_mov_b32_e32 v57, v127
	v_mov_b32_e32 v56, v127
	v_mov_b32_e32 v47, v127
	v_mov_b32_e32 v46, v127
	v_mov_b32_e32 v45, v127
	v_mov_b32_e32 v44, v127
	v_mov_b32_e32 v43, v127
	v_mov_b32_e32 v42, v127
	v_mov_b32_e32 v41, v127
	v_mov_b32_e32 v40, v127
	v_mov_b32_e32 v31, v127
	v_mov_b32_e32 v30, v127
	v_mov_b32_e32 v29, v127
	v_mov_b32_e32 v28, v127
	v_mov_b32_e32 v27, v127
	v_mov_b32_e32 v26, v127
	v_mov_b32_e32 v25, v127
	v_mov_b32_e32 v24, v127
	v_mov_b32_e32 v15, v127
	v_mov_b32_e32 v14, v127
	v_mov_b32_e32 v13, v127
	v_mov_b32_e32 v12, v127
	v_mov_b32_e32 v11, v127
	v_mov_b32_e32 v10, v127
	v_mov_b32_e32 v9, v127
	v_mov_b32_e32 v8, v127
	v_mov_b32_e32 v55, v127
	v_mov_b32_e32 v54, v127
	v_mov_b32_e32 v53, v127
	v_mov_b32_e32 v52, v127
	v_mov_b32_e32 v51, v127
	v_mov_b32_e32 v50, v127
	v_mov_b32_e32 v49, v127
	v_mov_b32_e32 v48, v127
	v_mov_b32_e32 v39, v127
	v_mov_b32_e32 v38, v127
	v_mov_b32_e32 v37, v127
	v_mov_b32_e32 v36, v127
	v_mov_b32_e32 v35, v127
	v_mov_b32_e32 v34, v127
	v_mov_b32_e32 v33, v127
	v_mov_b32_e32 v32, v127
	v_mov_b32_e32 v23, v127
	v_mov_b32_e32 v22, v127
	v_mov_b32_e32 v21, v127
	v_mov_b32_e32 v20, v127
	v_mov_b32_e32 v19, v127
	v_mov_b32_e32 v18, v127
	v_mov_b32_e32 v17, v127
	v_mov_b32_e32 v16, v127
	v_mov_b32_e32 v7, v127
	v_mov_b32_e32 v6, v127
	v_mov_b32_e32 v5, v127
	v_mov_b32_e32 v4, v127
	v_mov_b32_e32 v3, v127
	v_mov_b32_e32 v2, v127
	v_mov_b32_e32 v1, v127
	v_mov_b32_e32 v0, v127
	s_cbranch_vccnz .LBB0_675
	s_and_b64 s[46:47], s[4:5], exec
	s_cselect_b32 s29, s35, s45
	s_cselect_b32 s31, s34, s44
	s_cselect_b32 s70, s41, s43
	s_cselect_b32 s71, s40, s42
	v_ashrrev_i32_e32 v179, 31, v178
	s_add_u32 s72, s42, 0x100
	v_ashrrev_i32_e32 v177, 31, v176
	v_lshlrev_b64 v[0:1], 12, v[178:179]
	s_addc_u32 s73, s43, 0
	v_lshl_add_u64 v[180:181], v[176:177], 1, v[0:1]
	s_add_u32 s42, s44, 0x80080
	v_mov_b32_e32 v0, 0
	s_addc_u32 s43, s45, 0
	s_mov_b32 s44, 0
	v_mov_b32_e32 v1, v0
	s_cmp_lg_u32 s61, s44
	s_cbranch_scc1 .LBB0_673

;     __host__ __device__ bool next(int i, Unit& u) const { return i < cnt ? so.next(base + i, u) : false; }
;     __host__ __device__ bool next(int i, Unit& u) const { const int L = i * G + c; if (L >= 32) return false; u.g = L >> 3; u.pm = L & 7; u.pn = 0; return true; }
;   __device__ __forceinline__ bool next(int i,AttnUnit&u)const{ if(i>=4)return false; const int s=vcu&7; u.bh=vcu>>3; u.qb=(i==0)?s:(i==1)?15-s:(i==2)?16+s:31-s; return true; }
; template <class Epi, class Sched, bool ALIGN_EPI = false, bool SP2 = false>
; __device__ __forceinline__ void gemm_phase(PG8_LAS unsigned char* lds, const Gemm g, const Sched& S, const Epi& E) {
;     ...
;         const bool has_next = S.next(ui + 1, nxt);
;         const char* nA = has_next ? (const char*)(g.A + (size_t)nxt.g * g.gsA) + (size_t)nxt.pm * tstepA : cA; const char* nB = has_next ? (const char*)(g.Bt + (size_t)nxt.g * g.gsB) + (size_t)nxt.pn * tstepB : cB;
;         for (int t = 0; t < nt; t += 2) {
;             if constexpr (Epi::MIDK) { if (t == (nt >> 1)) { asm volatile("s_waitcnt vmcnt(0)" ::: "memory"); E.mid(acc, cur, wr, wc, fr, fq); asm volatile("s_waitcnt vmcnt(0)" ::: "memory"); } }
;             const bool last = (t == nt - 2);
;             const char* a1 = cA + (size_t)(t + 1) * kstep;
;             const char* a2 = last ? nA : cA + (size_t)(t + 2) * kstep; const char* b2 = last ? nB : cB + (size_t)(t + 2) * kstep;
;             const char* a3 = a2 + kstep; const char* b3 = b2 + kstep;
;     ...
; #pragma unroll
;         for (int a = 0; a < 2; ++a)
; #pragma unroll
;             for (int b = 0; b < 2; ++b)
; #pragma unroll
;                 for (int m = 0; m < 4; ++m)
; #pragma unroll
;                     for (int n = 0; n < 2; ++n) acc[a][b][m][n] = (f32x4){0.f, 0.f, 0.f, 0.f};
.LBB0_742:
	s_ashr_i32 s31, s30, 31
	s_lshl_b64 s[34:35], s[30:31], 20
	s_add_u32 s34, s39, s34
	s_addc_u32 s35, s48, s35
	s_ashr_i32 s29, s28, 31
	s_lshl_b64 s[36:37], s[28:29], 20
	s_add_u32 s36, s49, s36
	v_mov_b32_e32 v123, 0
	s_addc_u32 s37, s50, s37
	s_andn2_b64 vcc, exec, s[16:17]
	v_mov_b32_e32 v122, v123
	v_mov_b32_e32 v121, v123
	v_mov_b32_e32 v120, v123
	v_mov_b32_e32 v127, v123
	v_mov_b32_e32 v126, v123
	v_mov_b32_e32 v125, v123
	v_mov_b32_e32 v124, v123
	v_mov_b32_e32 v111, v123
	v_mov_b32_e32 v110, v123
	v_mov_b32_e32 v109, v123
	v_mov_b32_e32 v108, v123
	v_mov_b32_e32 v107, v123
	v_mov_b32_e32 v106, v123
	v_mov_b32_e32 v105, v123
	v_mov_b32_e32 v104, v123
	v_mov_b32_e32 v95, v123
	v_mov_b32_e32 v94, v123
	v_mov_b32_e32 v93, v123
	v_mov_b32_e32 v92, v123
	v_mov_b32_e32 v91, v123
	v_mov_b32_e32 v90, v123
	v_mov_b32_e32 v89, v123
	v_mov_b32_e32 v88, v123
	v_mov_b32_e32 v79, v123
	v_mov_b32_e32 v78, v123
	v_mov_b32_e32 v77, v123
	v_mov_b32_e32 v76, v123
	v_mov_b32_e32 v75, v123
	v_mov_b32_e32 v74, v123
	v_mov_b32_e32 v73, v123
	v_mov_b32_e32 v72, v123
	v_mov_b32_e32 v119, v123
	v_mov_b32_e32 v118, v123
	v_mov_b32_e32 v117, v123
	v_mov_b32_e32 v116, v123
	v_mov_b32_e32 v115, v123
	v_mov_b32_e32 v114, v123
	v_mov_b32_e32 v113, v123
	v_mov_b32_e32 v112, v123
	v_mov_b32_e32 v103, v123
	v_mov_b32_e32 v102, v123
	v_mov_b32_e32 v101, v123
	v_mov_b32_e32 v100, v123
	v_mov_b32_e32 v99, v123
	v_mov_b32_e32 v98, v123
	v_mov_b32_e32 v97, v123
	v_mov_b32_e32 v96, v123
	v_mov_b32_e32 v87, v123
	v_mov_b32_e32 v86, v123
	v_mov_b32_e32 v85, v123
	v_mov_b32_e32 v84, v123
	v_mov_b32_e32 v83, v123
	v_mov_b32_e32 v82, v123
	v_mov_b32_e32 v81, v123
	v_mov_b32_e32 v80, v123
	v_mov_b32_e32 v71, v123
	v_mov_b32_e32 v70, v123
	v_mov_b32_e32 v69, v123
	v_mov_b32_e32 v68, v123
	v_mov_b32_e32 v67, v123
	v_mov_b32_e32 v66, v123
	v_mov_b32_e32 v65, v123
	v_mov_b32_e32 v64, v123
	v_mov_b32_e32 v63, v123
	v_mov_b32_e32 v62, v123
	v_mov_b32_e32 v61, v123
	v_mov_b32_e32 v60, v123
	v_mov_b32_e32 v59, v123
	v_mov_b32_e32 v58, v123
	v_mov_b32_e32 v57, v123
	v_mov_b32_e32 v56, v123
	v_mov_b32_e32 v47, v123
	v_mov_b32_e32 v46, v123
	v_mov_b32_e32 v45, v123
	v_mov_b32_e32 v44, v123
	v_mov_b32_e32 v43, v123
	v_mov_b32_e32 v42, v123
	v_mov_b32_e32 v41, v123
	v_mov_b32_e32 v40, v123
	v_mov_b32_e32 v31, v123
	v_mov_b32_e32 v30, v123
	v_mov_b32_e32 v29, v123
	v_mov_b32_e32 v28, v123
	v_mov_b32_e32 v27, v123
	v_mov_b32_e32 v26, v123
	v_mov_b32_e32 v25, v123
	v_mov_b32_e32 v24, v123
	v_mov_b32_e32 v15, v123
	v_mov_b32_e32 v14, v123
	v_mov_b32_e32 v13, v123
	v_mov_b32_e32 v12, v123
	v_mov_b32_e32 v11, v123
	v_mov_b32_e32 v10, v123
	v_mov_b32_e32 v9, v123
	v_mov_b32_e32 v8, v123
	v_mov_b32_e32 v55, v123
	v_mov_b32_e32 v54, v123
	v_mov_b32_e32 v53, v123
	v_mov_b32_e32 v52, v123
	v_mov_b32_e32 v51, v123
	v_mov_b32_e32 v50, v123
	v_mov_b32_e32 v49, v123
	v_mov_b32_e32 v48, v123
	v_mov_b32_e32 v39, v123
	v_mov_b32_e32 v38, v123
	v_mov_b32_e32 v37, v123
	v_mov_b32_e32 v36, v123
	v_mov_b32_e32 v35, v123
	v_mov_b32_e32 v34, v123
	v_mov_b32_e32 v33, v123
	v_mov_b32_e32 v32, v123
	v_mov_b32_e32 v23, v123
	v_mov_b32_e32 v22, v123
	v_mov_b32_e32 v21, v123
	v_mov_b32_e32 v20, v123
	v_mov_b32_e32 v19, v123
	v_mov_b32_e32 v18, v123
	v_mov_b32_e32 v17, v123
	v_mov_b32_e32 v16, v123
	v_mov_b32_e32 v7, v123
	v_mov_b32_e32 v6, v123
	v_mov_b32_e32 v5, v123
	v_mov_b32_e32 v4, v123
	s_waitcnt lgkmcnt(0)
	v_mov_b32_e32 v3, v123
	v_mov_b32_e32 v2, v123
	v_mov_b32_e32 v1, v123
	v_mov_b32_e32 v0, v123
	s_cbranch_vccnz .LBB0_745
	s_and_b64 s[46:47], s[6:7], exec
	s_cselect_b32 s29, s35, s45
	s_cselect_b32 s31, s34, s44
	s_cselect_b32 s63, s37, s43
	s_cselect_b32 s64, s36, s42
	s_add_u32 s65, s42, 0x100
	s_addc_u32 s66, s43, 0
	s_add_u32 s42, s44, 0x80080
	s_addc_u32 s43, s45, 0
	s_mov_b32 s44, 0

;     __host__ __device__ bool next(int i, Unit& u) const { return i < cnt ? so.next(base + i, u) : false; }
;     __host__ __device__ bool next(int i, Unit& u) const { const int L = i * G + c; if (L >= 32) return false; u.g = L >> 3; u.pm = L & 7; u.pn = 0; return true; }
;   __device__ __forceinline__ bool next(int i,AttnUnit&u)const{ if(i>=4)return false; const int s=vcu&7; u.bh=vcu>>3; u.qb=(i==0)?s:(i==1)?15-s:(i==2)?16+s:31-s; return true; }
; template <class Epi, class Sched, bool ALIGN_EPI = false, bool SP2 = false>
; __device__ __forceinline__ void gemm_phase(PG8_LAS unsigned char* lds, const Gemm g, const Sched& S, const Epi& E) {
;     ...
;         const bool has_next = S.next(ui + 1, nxt);
;         const char* nA = has_next ? (const char*)(g.A + (size_t)nxt.g * g.gsA) + (size_t)nxt.pm * tstepA : cA; const char* nB = has_next ? (const char*)(g.Bt + (size_t)nxt.g * g.gsB) + (size_t)nxt.pn * tstepB : cB;
;         for (int t = 0; t < nt; t += 2) {
;             if constexpr (Epi::MIDK) { if (t == (nt >> 1)) { asm volatile("s_waitcnt vmcnt(0)" ::: "memory"); E.mid(acc, cur, wr, wc, fr, fq); asm volatile("s_waitcnt vmcnt(0)" ::: "memory"); } }
;             const bool last = (t == nt - 2);
;             const char* a1 = cA + (size_t)(t + 1) * kstep;
;             const char* a2 = last ? nA : cA + (size_t)(t + 2) * kstep; const char* b2 = last ? nB : cB + (size_t)(t + 2) * kstep;
;             const char* a3 = a2 + kstep; const char* b3 = b2 + kstep;
;     ...
; #pragma unroll
;         for (int a = 0; a < 2; ++a)
; #pragma unroll
;             for (int b = 0; b < 2; ++b)
; #pragma unroll
;                 for (int m = 0; m < 4; ++m)
; #pragma unroll
;                     for (int n = 0; n < 2; ++n) acc[a][b][m][n] = (f32x4){0.f, 0.f, 0.f, 0.f};
.LBB0_827:
	s_ashr_i32 s35, s34, 31
	s_lshl_b64 s[36:37], s[34:35], 20
	s_add_u32 s36, s47, s36
	s_addc_u32 s37, s48, s37
	s_ashr_i32 s31, s30, 31
	s_lshl_b64 s[38:39], s[30:31], 20
	s_add_u32 s38, s49, s38
	v_mov_b32_e32 v123, 0
	s_addc_u32 s39, s50, s39
	s_andn2_b64 vcc, exec, s[18:19]
	v_mov_b32_e32 v122, v123
	v_mov_b32_e32 v121, v123
	v_mov_b32_e32 v120, v123
	v_mov_b32_e32 v127, v123
	v_mov_b32_e32 v126, v123
	v_mov_b32_e32 v125, v123
	v_mov_b32_e32 v124, v123
	v_mov_b32_e32 v111, v123
	v_mov_b32_e32 v110, v123
	v_mov_b32_e32 v109, v123
	v_mov_b32_e32 v108, v123
	v_mov_b32_e32 v107, v123
	v_mov_b32_e32 v106, v123
	v_mov_b32_e32 v105, v123
	v_mov_b32_e32 v104, v123
	v_mov_b32_e32 v95, v123
	v_mov_b32_e32 v94, v123
	v_mov_b32_e32 v93, v123
	v_mov_b32_e32 v92, v123
	v_mov_b32_e32 v91, v123
	v_mov_b32_e32 v90, v123
	v_mov_b32_e32 v89, v123
	v_mov_b32_e32 v88, v123
	v_mov_b32_e32 v79, v123
	v_mov_b32_e32 v78, v123
	v_mov_b32_e32 v77, v123
	v_mov_b32_e32 v76, v123
	v_mov_b32_e32 v75, v123
	v_mov_b32_e32 v74, v123
	v_mov_b32_e32 v73, v123
	v_mov_b32_e32 v72, v123
	v_mov_b32_e32 v119, v123
	v_mov_b32_e32 v118, v123
	v_mov_b32_e32 v117, v123
	v_mov_b32_e32 v116, v123
	v_mov_b32_e32 v115, v123
	v_mov_b32_e32 v114, v123
	v_mov_b32_e32 v113, v123
	v_mov_b32_e32 v112, v123
	v_mov_b32_e32 v103, v123
	v_mov_b32_e32 v102, v123
	v_mov_b32_e32 v101, v123
	v_mov_b32_e32 v100, v123
	v_mov_b32_e32 v99, v123
	v_mov_b32_e32 v98, v123
	v_mov_b32_e32 v97, v123
	v_mov_b32_e32 v96, v123
	v_mov_b32_e32 v87, v123
	v_mov_b32_e32 v86, v123
	v_mov_b32_e32 v85, v123
	v_mov_b32_e32 v84, v123
	v_mov_b32_e32 v83, v123
	v_mov_b32_e32 v82, v123
	v_mov_b32_e32 v81, v123
	v_mov_b32_e32 v80, v123
	v_mov_b32_e32 v71, v123
	v_mov_b32_e32 v70, v123
	v_mov_b32_e32 v69, v123
	v_mov_b32_e32 v68, v123
	v_mov_b32_e32 v67, v123
	v_mov_b32_e32 v66, v123
	v_mov_b32_e32 v65, v123
	v_mov_b32_e32 v64, v123
	v_mov_b32_e32 v63, v123
	v_mov_b32_e32 v62, v123
	v_mov_b32_e32 v61, v123
	v_mov_b32_e32 v60, v123
	v_mov_b32_e32 v59, v123
	v_mov_b32_e32 v58, v123
	v_mov_b32_e32 v57, v123
	v_mov_b32_e32 v56, v123
	v_mov_b32_e32 v47, v123
	v_mov_b32_e32 v46, v123
	v_mov_b32_e32 v45, v123
	v_mov_b32_e32 v44, v123
	v_mov_b32_e32 v43, v123
	v_mov_b32_e32 v42, v123
	v_mov_b32_e32 v41, v123
	v_mov_b32_e32 v40, v123
	v_mov_b32_e32 v31, v123
	v_mov_b32_e32 v30, v123
	v_mov_b32_e32 v29, v123
	v_mov_b32_e32 v28, v123
	v_mov_b32_e32 v27, v123
	v_mov_b32_e32 v26, v123
	v_mov_b32_e32 v25, v123
	v_mov_b32_e32 v24, v123
	v_mov_b32_e32 v15, v123
	v_mov_b32_e32 v14, v123
	v_mov_b32_e32 v13, v123
	v_mov_b32_e32 v12, v123
	v_mov_b32_e32 v11, v123
	v_mov_b32_e32 v10, v123
	v_mov_b32_e32 v9, v123
	v_mov_b32_e32 v8, v123
	v_mov_b32_e32 v55, v123
	v_mov_b32_e32 v54, v123
	v_mov_b32_e32 v53, v123
	v_mov_b32_e32 v52, v123
	v_mov_b32_e32 v51, v123
	v_mov_b32_e32 v50, v123
	v_mov_b32_e32 v49, v123
	v_mov_b32_e32 v48, v123
	v_mov_b32_e32 v39, v123
	v_mov_b32_e32 v38, v123
	v_mov_b32_e32 v37, v123
	v_mov_b32_e32 v36, v123
	v_mov_b32_e32 v35, v123
	v_mov_b32_e32 v34, v123
	v_mov_b32_e32 v33, v123
	v_mov_b32_e32 v32, v123
	v_mov_b32_e32 v23, v123
	v_mov_b32_e32 v22, v123
	v_mov_b32_e32 v21, v123
	v_mov_b32_e32 v20, v123
	v_mov_b32_e32 v19, v123
	v_mov_b32_e32 v18, v123
	v_mov_b32_e32 v17, v123
	v_mov_b32_e32 v16, v123
	v_mov_b32_e32 v7, v123
	v_mov_b32_e32 v6, v123
	v_mov_b32_e32 v5, v123
	v_mov_b32_e32 v4, v123
	v_mov_b32_e32 v3, v123
	v_mov_b32_e32 v2, v123
	v_mov_b32_e32 v1, v123
	v_mov_b32_e32 v0, v123
	s_cbranch_vccnz .LBB0_830
	s_and_b64 s[44:45], s[6:7], exec
	s_cselect_b32 s31, s37, s43
	s_cselect_b32 s35, s36, s42
	s_cselect_b32 s67, s39, s41
	s_cselect_b32 s68, s38, s40
	s_add_u32 s69, s40, 0x100
	s_addc_u32 s70, s41, 0
	s_add_u32 s40, s42, 0x80080
	s_addc_u32 s41, s43, 0
	s_mov_b32 s42, 0

;     __host__ __device__ bool next(int i, Unit& u) const { return i < cnt ? so.next(base + i, u) : false; }
;     __host__ __device__ bool next(int i, Unit& u) const { const int L = i * G + c; if (L >= 32) return false; u.g = L >> 3; u.pm = L & 7; u.pn = 0; return true; }
;   __device__ __forceinline__ bool next(int i,AttnUnit&u)const{ if(i>=4)return false; const int s=vcu&7; u.bh=vcu>>3; u.qb=(i==0)?s:(i==1)?15-s:(i==2)?16+s:31-s; return true; }
; template <class Epi, class Sched, bool ALIGN_EPI = false, bool SP2 = false>
; __device__ __forceinline__ void gemm_phase(PG8_LAS unsigned char* lds, const Gemm g, const Sched& S, const Epi& E) {
;     ...
;         const bool has_next = S.next(ui + 1, nxt);
;         const char* nA = has_next ? (const char*)(g.A + (size_t)nxt.g * g.gsA) + (size_t)nxt.pm * tstepA : cA; const char* nB = has_next ? (const char*)(g.Bt + (size_t)nxt.g * g.gsB) + (size_t)nxt.pn * tstepB : cB;
;         for (int t = 0; t < nt; t += 2) {
;             if constexpr (Epi::MIDK) { if (t == (nt >> 1)) { asm volatile("s_waitcnt vmcnt(0)" ::: "memory"); E.mid(acc, cur, wr, wc, fr, fq); asm volatile("s_waitcnt vmcnt(0)" ::: "memory"); } }
;             const bool last = (t == nt - 2);
;             const char* a1 = cA + (size_t)(t + 1) * kstep;
;             const char* a2 = last ? nA : cA + (size_t)(t + 2) * kstep; const char* b2 = last ? nB : cB + (size_t)(t + 2) * kstep;
;             const char* a3 = a2 + kstep; const char* b3 = b2 + kstep;
;     ...
; #pragma unroll
;         for (int a = 0; a < 2; ++a)
; #pragma unroll
;             for (int b = 0; b < 2; ++b)
; #pragma unroll
;                 for (int m = 0; m < 4; ++m)
; #pragma unroll
;                     for (int n = 0; n < 2; ++n) acc[a][b][m][n] = (f32x4){0.f, 0.f, 0.f, 0.f};
.LBB0_897:
	s_ashr_i32 s29, s28, 31
	s_lshl_b64 s[30:31], s[28:29], 22
	s_add_u32 s30, s45, s30
	s_addc_u32 s31, s46, s31
	s_ashr_i32 s27, s26, 31
	s_lshl_b64 s[34:35], s[26:27], 22
	s_add_u32 s34, s47, s34
	v_mov_b32_e32 v127, 0
	s_addc_u32 s35, s48, s35
	s_andn2_b64 vcc, exec, s[12:13]
	v_mov_b32_e32 v126, v127
	v_mov_b32_e32 v125, v127
	v_mov_b32_e32 v124, v127
	v_mov_b32_e32 v123, v127
	v_mov_b32_e32 v122, v127
	v_mov_b32_e32 v121, v127
	v_mov_b32_e32 v120, v127
	v_mov_b32_e32 v111, v127
	v_mov_b32_e32 v110, v127
	v_mov_b32_e32 v109, v127
	v_mov_b32_e32 v108, v127
	v_mov_b32_e32 v107, v127
	v_mov_b32_e32 v106, v127
	v_mov_b32_e32 v105, v127
	v_mov_b32_e32 v104, v127
	v_mov_b32_e32 v95, v127
	v_mov_b32_e32 v94, v127
	v_mov_b32_e32 v93, v127
	v_mov_b32_e32 v92, v127
	v_mov_b32_e32 v91, v127
	v_mov_b32_e32 v90, v127
	v_mov_b32_e32 v89, v127
	v_mov_b32_e32 v88, v127
	v_mov_b32_e32 v79, v127
	v_mov_b32_e32 v78, v127
	v_mov_b32_e32 v77, v127
	v_mov_b32_e32 v76, v127
	v_mov_b32_e32 v75, v127
	v_mov_b32_e32 v74, v127
	v_mov_b32_e32 v73, v127
	v_mov_b32_e32 v72, v127
	v_mov_b32_e32 v119, v127
	v_mov_b32_e32 v118, v127
	v_mov_b32_e32 v117, v127
	v_mov_b32_e32 v116, v127
	v_mov_b32_e32 v115, v127
	v_mov_b32_e32 v114, v127
	v_mov_b32_e32 v113, v127
	v_mov_b32_e32 v112, v127
	v_mov_b32_e32 v103, v127
	v_mov_b32_e32 v102, v127
	v_mov_b32_e32 v101, v127
	v_mov_b32_e32 v100, v127
	v_mov_b32_e32 v99, v127
	v_mov_b32_e32 v98, v127
	v_mov_b32_e32 v97, v127
	v_mov_b32_e32 v96, v127
	v_mov_b32_e32 v87, v127
	v_mov_b32_e32 v86, v127
	v_mov_b32_e32 v85, v127
	v_mov_b32_e32 v84, v127
	v_mov_b32_e32 v83, v127
	v_mov_b32_e32 v82, v127
	v_mov_b32_e32 v81, v127
	v_mov_b32_e32 v80, v127
	v_mov_b32_e32 v71, v127
	v_mov_b32_e32 v70, v127
	v_mov_b32_e32 v69, v127
	v_mov_b32_e32 v68, v127
	v_mov_b32_e32 v67, v127
	v_mov_b32_e32 v66, v127
	v_mov_b32_e32 v65, v127
	v_mov_b32_e32 v64, v127
	v_mov_b32_e32 v63, v127
	v_mov_b32_e32 v62, v127
	v_mov_b32_e32 v61, v127
	v_mov_b32_e32 v60, v127
	v_mov_b32_e32 v59, v127
	v_mov_b32_e32 v58, v127
	v_mov_b32_e32 v57, v127
	v_mov_b32_e32 v56, v127
	v_mov_b32_e32 v47, v127
	v_mov_b32_e32 v46, v127
	v_mov_b32_e32 v45, v127
	v_mov_b32_e32 v44, v127
	v_mov_b32_e32 v43, v127
	v_mov_b32_e32 v42, v127
	v_mov_b32_e32 v41, v127
	v_mov_b32_e32 v40, v127
	v_mov_b32_e32 v31, v127
	v_mov_b32_e32 v30, v127
	v_mov_b32_e32 v29, v127
	v_mov_b32_e32 v28, v127
	v_mov_b32_e32 v27, v127
	v_mov_b32_e32 v26, v127
	v_mov_b32_e32 v25, v127
	v_mov_b32_e32 v24, v127
	v_mov_b32_e32 v15, v127
	v_mov_b32_e32 v14, v127
	v_mov_b32_e32 v13, v127
	v_mov_b32_e32 v12, v127
	v_mov_b32_e32 v11, v127
	v_mov_b32_e32 v10, v127
	v_mov_b32_e32 v9, v127
	v_mov_b32_e32 v8, v127
	v_mov_b32_e32 v55, v127
	v_mov_b32_e32 v54, v127
	v_mov_b32_e32 v53, v127
	v_mov_b32_e32 v52, v127
	v_mov_b32_e32 v51, v127
	v_mov_b32_e32 v50, v127
	v_mov_b32_e32 v49, v127
	v_mov_b32_e32 v48, v127
	v_mov_b32_e32 v39, v127
	v_mov_b32_e32 v38, v127
	v_mov_b32_e32 v37, v127
	v_mov_b32_e32 v36, v127
	v_mov_b32_e32 v35, v127
	v_mov_b32_e32 v34, v127
	v_mov_b32_e32 v33, v127
	v_mov_b32_e32 v32, v127
	v_mov_b32_e32 v23, v127
	v_mov_b32_e32 v22, v127
	v_mov_b32_e32 v21, v127
	v_mov_b32_e32 v20, v127
	v_mov_b32_e32 v19, v127
	v_mov_b32_e32 v18, v127
	v_mov_b32_e32 v17, v127
	v_mov_b32_e32 v16, v127
	v_mov_b32_e32 v7, v127
	v_mov_b32_e32 v6, v127
	v_mov_b32_e32 v5, v127
	v_mov_b32_e32 v4, v127
	s_waitcnt lgkmcnt(0)
	v_mov_b32_e32 v3, v127
	v_mov_b32_e32 v2, v127
	v_mov_b32_e32 v1, v127
	v_mov_b32_e32 v0, v127
	s_cbranch_vccnz .LBB0_900
	s_and_b64 s[42:43], s[6:7], exec
	s_cselect_b32 s27, s31, s41
	s_cselect_b32 s29, s30, s40
	s_cselect_b32 s65, s35, s39
	s_cselect_b32 s66, s34, s38
	s_add_u32 s67, s38, 0x100
	s_addc_u32 s68, s39, 0
	s_add_u32 s38, s40, 0x200080
	s_addc_u32 s39, s41, 0
	s_mov_b32 s40, 0

;     __host__ __device__ bool next(int i, Unit& u) const { return i < cnt ? so.next(base + i, u) : false; }
;     __host__ __device__ bool next(int i, Unit& u) const { const int L = i * G + c; if (L >= 32) return false; u.g = L >> 3; u.pm = L & 7; u.pn = 0; return true; }
;   __device__ __forceinline__ bool next(int i,AttnUnit&u)const{ if(i>=4)return false; const int s=vcu&7; u.bh=vcu>>3; u.qb=(i==0)?s:(i==1)?15-s:(i==2)?16+s:31-s; return true; }
; template <class Epi, class Sched, bool ALIGN_EPI = false, bool SP2 = false>
; __device__ __forceinline__ void gemm_phase(PG8_LAS unsigned char* lds, const Gemm g, const Sched& S, const Epi& E) {
;     ...
;         const bool has_next = S.next(ui + 1, nxt);
;         const char* nA = has_next ? (const char*)(g.A + (size_t)nxt.g * g.gsA) + (size_t)nxt.pm * tstepA : cA; const char* nB = has_next ? (const char*)(g.Bt + (size_t)nxt.g * g.gsB) + (size_t)nxt.pn * tstepB : cB;
;         for (int t = 0; t < nt; t += 2) {
;             if constexpr (Epi::MIDK) { if (t == (nt >> 1)) { asm volatile("s_waitcnt vmcnt(0)" ::: "memory"); E.mid(acc, cur, wr, wc, fr, fq); asm volatile("s_waitcnt vmcnt(0)" ::: "memory"); } }
;             const bool last = (t == nt - 2);
;             const char* a1 = cA + (size_t)(t + 1) * kstep;
;             const char* a2 = last ? nA : cA + (size_t)(t + 2) * kstep; const char* b2 = last ? nB : cB + (size_t)(t + 2) * kstep;
;             const char* a3 = a2 + kstep; const char* b3 = b2 + kstep;
;     ...
; #pragma unroll
;         for (int a = 0; a < 2; ++a)
; #pragma unroll
;             for (int b = 0; b < 2; ++b)
; #pragma unroll
;                 for (int m = 0; m < 4; ++m)
; #pragma unroll
;                     for (int n = 0; n < 2; ++n) acc[a][b][m][n] = (f32x4){0.f, 0.f, 0.f, 0.f};
.LBB0_986:
	s_ashr_i32 s35, s34, 31
	s_lshl_b64 s[36:37], s[34:35], 17
	s_add_u32 s36, s48, s36
	s_addc_u32 s37, s49, s37
	s_ashr_i32 s31, s30, 31
	s_lshl_b64 s[38:39], s[30:31], 17
	s_add_u32 s38, s50, s38
	v_mov_b32_e32 v127, 0
	s_addc_u32 s39, s51, s39
	s_and_b64 vcc, exec, s[6:7]
	v_mov_b32_e32 v126, v127
	v_mov_b32_e32 v125, v127
	v_mov_b32_e32 v124, v127
	v_mov_b32_e32 v123, v127
	v_mov_b32_e32 v122, v127
	v_mov_b32_e32 v121, v127
	v_mov_b32_e32 v120, v127
	v_mov_b32_e32 v111, v127
	v_mov_b32_e32 v110, v127
	v_mov_b32_e32 v109, v127
	v_mov_b32_e32 v108, v127
	v_mov_b32_e32 v107, v127
	v_mov_b32_e32 v106, v127
	v_mov_b32_e32 v105, v127
	v_mov_b32_e32 v104, v127
	v_mov_b32_e32 v95, v127
	v_mov_b32_e32 v94, v127
	v_mov_b32_e32 v93, v127
	v_mov_b32_e32 v92, v127
	v_mov_b32_e32 v91, v127
	v_mov_b32_e32 v90, v127
	v_mov_b32_e32 v89, v127
	v_mov_b32_e32 v88, v127
	v_mov_b32_e32 v79, v127
	v_mov_b32_e32 v78, v127
	v_mov_b32_e32 v77, v127
	v_mov_b32_e32 v76, v127
	v_mov_b32_e32 v75, v127
	v_mov_b32_e32 v74, v127
	v_mov_b32_e32 v73, v127
	v_mov_b32_e32 v72, v127
	v_mov_b32_e32 v119, v127
	v_mov_b32_e32 v118, v127
	v_mov_b32_e32 v117, v127
	v_mov_b32_e32 v116, v127
	v_mov_b32_e32 v115, v127
	v_mov_b32_e32 v114, v127
	v_mov_b32_e32 v113, v127
	v_mov_b32_e32 v112, v127
	v_mov_b32_e32 v103, v127
	v_mov_b32_e32 v102, v127
	v_mov_b32_e32 v101, v127
	v_mov_b32_e32 v100, v127
	v_mov_b32_e32 v99, v127
	v_mov_b32_e32 v98, v127
	v_mov_b32_e32 v97, v127
	v_mov_b32_e32 v96, v127
	v_mov_b32_e32 v87, v127
	v_mov_b32_e32 v86, v127
	v_mov_b32_e32 v85, v127
	v_mov_b32_e32 v84, v127
	v_mov_b32_e32 v83, v127
	v_mov_b32_e32 v82, v127
	v_mov_b32_e32 v81, v127
	v_mov_b32_e32 v80, v127
	v_mov_b32_e32 v71, v127
	v_mov_b32_e32 v70, v127
	v_mov_b32_e32 v69, v127
	v_mov_b32_e32 v68, v127
	v_mov_b32_e32 v67, v127
	v_mov_b32_e32 v66, v127
	v_mov_b32_e32 v65, v127
	v_mov_b32_e32 v64, v127
	v_mov_b32_e32 v63, v127
	v_mov_b32_e32 v62, v127
	v_mov_b32_e32 v61, v127
	v_mov_b32_e32 v60, v127
	v_mov_b32_e32 v59, v127
	v_mov_b32_e32 v58, v127
	v_mov_b32_e32 v57, v127
	v_mov_b32_e32 v56, v127
	v_mov_b32_e32 v47, v127
	v_mov_b32_e32 v46, v127
	v_mov_b32_e32 v45, v127
	v_mov_b32_e32 v44, v127
	v_mov_b32_e32 v43, v127
	v_mov_b32_e32 v42, v127
	v_mov_b32_e32 v41, v127
	v_mov_b32_e32 v40, v127
	v_mov_b32_e32 v31, v127
	v_mov_b32_e32 v30, v127
	v_mov_b32_e32 v29, v127
	v_mov_b32_e32 v28, v127
	v_mov_b32_e32 v27, v127
	v_mov_b32_e32 v26, v127
	v_mov_b32_e32 v25, v127
	v_mov_b32_e32 v24, v127
	v_mov_b32_e32 v15, v127
	v_mov_b32_e32 v14, v127
	v_mov_b32_e32 v13, v127
	v_mov_b32_e32 v12, v127
	v_mov_b32_e32 v11, v127
	v_mov_b32_e32 v10, v127
	v_mov_b32_e32 v9, v127
	v_mov_b32_e32 v8, v127
	v_mov_b32_e32 v55, v127
	v_mov_b32_e32 v54, v127
	v_mov_b32_e32 v53, v127
	v_mov_b32_e32 v52, v127
	v_mov_b32_e32 v51, v127
	v_mov_b32_e32 v50, v127
	v_mov_b32_e32 v49, v127
	v_mov_b32_e32 v48, v127
	v_mov_b32_e32 v39, v127
	v_mov_b32_e32 v38, v127
	v_mov_b32_e32 v37, v127
	v_mov_b32_e32 v36, v127
	v_mov_b32_e32 v35, v127
	v_mov_b32_e32 v34, v127
	v_mov_b32_e32 v33, v127
	v_mov_b32_e32 v32, v127
	v_mov_b32_e32 v23, v127
	v_mov_b32_e32 v22, v127
	v_mov_b32_e32 v21, v127
	v_mov_b32_e32 v20, v127
	v_mov_b32_e32 v19, v127
	v_mov_b32_e32 v18, v127
	v_mov_b32_e32 v17, v127
	v_mov_b32_e32 v16, v127
	v_mov_b32_e32 v7, v127
	v_mov_b32_e32 v6, v127
	v_mov_b32_e32 v5, v127
	v_mov_b32_e32 v4, v127
	v_mov_b32_e32 v3, v127
	v_mov_b32_e32 v2, v127
	v_mov_b32_e32 v1, v127
	v_mov_b32_e32 v0, v127
	s_cbranch_vccnz .LBB0_989
	s_and_b64 s[44:45], s[8:9], exec
	s_cselect_b32 s31, s37, s43
	s_cselect_b32 s35, s36, s42
	s_cselect_b32 s67, s39, s41
	s_cselect_b32 s68, s38, s40
	s_add_u32 s69, s40, 0x100
	s_addc_u32 s70, s41, 0
	s_add_u32 s40, s42, 0x10080
	s_addc_u32 s41, s43, 0
	s_mov_b32 s42, 0
